# global grid barriers: 8th-from-last arriver of each XCD issues an early L2 writeback (v54 + firstwb K=8)
# speedup vs baseline: 1.0019x; 1.0019x over previous
.LBB0_182:
	s_or_b64 exec, exec, s[12:13]
	v_cvt_f32_u32_e32 v4, v2
	s_waitcnt vmcnt(0)
	v_readfirstlane_b32 s10, v3
	v_sub_u32_e32 v3, 0, v2
	v_rcp_iflag_f32_e32 v4, v4
	v_add_u32_e32 v5, s10, v1
	v_mul_f32_e32 v4, 0x4f7ffffe, v4
	v_cvt_u32_f32_e32 v4, v4
	v_mul_lo_u32 v1, v3, v4
	v_mul_hi_u32 v1, v4, v1
	v_add_u32_e32 v1, v4, v1
	v_mul_hi_u32 v1, v5, v1
	v_mul_lo_u32 v3, v1, v2
	v_sub_u32_e32 v3, v5, v3
	v_add_u32_e32 v4, 1, v1
	v_cmp_ge_u32_e32 vcc, v3, v2
	s_nop 1
	v_cndmask_b32_e32 v1, v1, v4, vcc
	v_sub_u32_e32 v4, v3, v2
	v_cndmask_b32_e32 v3, v3, v4, vcc
	v_add_u32_e32 v4, 1, v1
	v_cmp_ge_u32_e32 vcc, v3, v2
	v_add_u32_e32 v3, 1, v5
	s_nop 0
	v_cndmask_b32_e32 v1, v1, v4, vcc
	v_mul_lo_u32 v4, v2, v1
	v_add_u32_e32 v2, v4, v2
	v_cmp_ne_u32_e32 vcc, v3, v2
	s_and_saveexec_b64 s[10:11], vcc
	s_xor_b64 s[10:11], exec, s[10:11]
	s_cbranch_execz .LBB0_196
	v_add_u32_e32 v0, 8, v5
	v_cmp_eq_u32_e32 vcc, v0, v2
	s_and_b64 vcc, exec, vcc
	s_cbranch_vccz .Lfirstwb_skip_0
	buffer_wbl2 sc1
.Lfirstwb_skip_0:
	s_waitcnt lgkmcnt(0)
	v_mov_b32_e32 v0, 0x2000
	global_load_dword v0, v0, s[8:9] offset:1024 sc1
	buffer_inv sc1
	s_add_u32 s16, s8, 0x2400
	s_addc_u32 s17, s9, 0
	s_waitcnt vmcnt(0)
	v_cmp_eq_u32_e32 vcc, v0, v1
	s_and_saveexec_b64 s[12:13], vcc
	s_cbranch_execz .LBB0_195
	s_add_u32 s14, s6, 0x4200
	s_addc_u32 s15, s7, 0
	s_mov_b32 s28, 1
	s_mov_b64 s[18:19], 0
	v_mov_b32_e32 v0, 0
	s_branch .LBB0_186

.Lfirstwb_skip_2:
	s_waitcnt lgkmcnt(0)
	v_mov_b32_e32 v0, 0x2000
	global_load_dword v0, v0, s[8:9] offset:1024 sc1
	buffer_inv sc1
	s_add_u32 s18, s8, 0x2400
	s_addc_u32 s19, s9, 0
	s_waitcnt vmcnt(0)
	v_cmp_eq_u32_e32 vcc, v0, v1
	s_and_saveexec_b64 s[12:13], vcc
	s_cbranch_execz .LBB0_494
	s_add_u32 s16, s6, 0x4200
	s_addc_u32 s17, s7, 0
	s_mov_b32 s30, 1
	s_mov_b64 s[20:21], 0
	v_mov_b32_e32 v0, 0
	s_branch .LBB0_485

.LBB0_1296:
	s_or_b64 exec, exec, s[16:17]
	v_cvt_f32_u32_e32 v4, v2
	s_waitcnt vmcnt(0)
	v_readfirstlane_b32 s12, v3
	v_sub_u32_e32 v3, 0, v2
	v_rcp_iflag_f32_e32 v4, v4
	v_add_u32_e32 v5, s12, v1
	v_mul_f32_e32 v4, 0x4f7ffffe, v4
	v_cvt_u32_f32_e32 v4, v4
	v_mul_lo_u32 v1, v3, v4
	v_mul_hi_u32 v1, v4, v1
	v_add_u32_e32 v1, v4, v1
	v_mul_hi_u32 v1, v5, v1
	v_mul_lo_u32 v3, v1, v2
	v_sub_u32_e32 v3, v5, v3
	v_add_u32_e32 v4, 1, v1
	v_cmp_ge_u32_e32 vcc, v3, v2
	s_nop 1
	v_cndmask_b32_e32 v1, v1, v4, vcc
	v_sub_u32_e32 v4, v3, v2
	v_cndmask_b32_e32 v3, v3, v4, vcc
	v_add_u32_e32 v4, 1, v1
	v_cmp_ge_u32_e32 vcc, v3, v2
	v_add_u32_e32 v3, 1, v5
	s_nop 0
	v_cndmask_b32_e32 v1, v1, v4, vcc
	v_mul_lo_u32 v4, v2, v1
	v_add_u32_e32 v2, v4, v2
	v_cmp_ne_u32_e32 vcc, v3, v2
	s_and_saveexec_b64 s[12:13], vcc
	s_xor_b64 s[12:13], exec, s[12:13]
	s_cbranch_execz .LBB0_1310
	v_add_u32_e32 v0, 8, v5
	v_cmp_eq_u32_e32 vcc, v0, v2
	s_and_b64 vcc, exec, vcc
	s_cbranch_vccz .Lfirstwb_skip_4
	buffer_wbl2 sc1
.Lfirstwb_skip_4:
	s_waitcnt lgkmcnt(0)
	v_mov_b32_e32 v0, 0x2000
	global_load_dword v0, v0, s[10:11] offset:1024 sc1
	buffer_inv sc1
	s_add_u32 s20, s10, 0x2400
	s_addc_u32 s21, s11, 0
	s_waitcnt vmcnt(0)
	v_cmp_eq_u32_e32 vcc, v0, v1
	s_and_saveexec_b64 s[16:17], vcc
	s_cbranch_execz .LBB0_1309
	s_add_u32 s18, s8, 0x4200
	s_addc_u32 s19, s9, 0
	s_mov_b32 s33, 1
	s_mov_b64 s[22:23], 0
	v_mov_b32_e32 v0, 0
	s_branch .LBB0_1300

.LBB0_1953:
	s_or_b64 exec, exec, s[14:15]
	v_cvt_f32_u32_e32 v4, v2
	s_waitcnt vmcnt(0)
	v_readfirstlane_b32 s12, v3
	v_sub_u32_e32 v3, 0, v2
	v_rcp_iflag_f32_e32 v4, v4
	v_add_u32_e32 v5, s12, v1
	v_mul_f32_e32 v4, 0x4f7ffffe, v4
	v_cvt_u32_f32_e32 v4, v4
	v_mul_lo_u32 v1, v3, v4
	v_mul_hi_u32 v1, v4, v1
	v_add_u32_e32 v1, v4, v1
	v_mul_hi_u32 v1, v5, v1
	v_mul_lo_u32 v3, v1, v2
	v_sub_u32_e32 v3, v5, v3
	v_add_u32_e32 v4, 1, v1
	v_cmp_ge_u32_e32 vcc, v3, v2
	s_nop 1
	v_cndmask_b32_e32 v1, v1, v4, vcc
	v_sub_u32_e32 v4, v3, v2
	v_cndmask_b32_e32 v3, v3, v4, vcc
	v_add_u32_e32 v4, 1, v1
	v_cmp_ge_u32_e32 vcc, v3, v2
	v_add_u32_e32 v3, 1, v5
	s_nop 0
	v_cndmask_b32_e32 v1, v1, v4, vcc
	v_mul_lo_u32 v4, v2, v1
	v_add_u32_e32 v2, v4, v2
	v_cmp_ne_u32_e32 vcc, v3, v2
	s_and_saveexec_b64 s[12:13], vcc
	s_xor_b64 s[12:13], exec, s[12:13]
	s_cbranch_execz .LBB0_1967
	v_add_u32_e32 v0, 8, v5
	v_cmp_eq_u32_e32 vcc, v0, v2
	s_and_b64 vcc, exec, vcc
	s_cbranch_vccz .Lfirstwb_skip_6
	buffer_wbl2 sc1
.Lfirstwb_skip_6:
	s_waitcnt lgkmcnt(0)
	v_mov_b32_e32 v0, 0x2000
	global_load_dword v0, v0, s[10:11] offset:1024 sc1
	buffer_inv sc1
	s_add_u32 s18, s10, 0x2400
	s_addc_u32 s19, s11, 0
	s_waitcnt vmcnt(0)
	v_cmp_eq_u32_e32 vcc, v0, v1
	s_and_saveexec_b64 s[14:15], vcc
	s_cbranch_execz .LBB0_1966
	s_add_u32 s16, s8, 0x4200
	s_addc_u32 s17, s9, 0
	s_mov_b32 s30, 1
	s_mov_b64 s[20:21], 0
	v_mov_b32_e32 v0, 0
	s_branch .LBB0_1957
